# GEMM: per-tile static-order step uses shift/mask for the group-size division (group size is 4 or 8 for these shapes)
# baseline (speedup 1.0000x reference)
;     __host__ __device__ bool next(int i, Unit& u) const {
;     ...
;         int wgid = (int)L; { const int q = nwg / NXCD, r = nwg % NXCD, xcd = wgid % NXCD, off = wgid / NXCD; wgid = (xcd < r ? xcd * (q + 1) : r * (q + 1) + (xcd - r) * q) + off; }
;         const int nig = WGM * nN, gid = wgid / nig, fm = gid * WGM, gsz = (nM - fm) < WGM ? (nM - fm) : WGM;
;         u.pm = fm + ((wgid % nig) % gsz); u.pn = (wgid % nig) / gsz; return true;
.LBB0_240:
	s_ashr_i32 s1, s1, 3
	s_add_i32 s1, s31, s1
	s_ashr_i32 s30, s1, 31
	s_lshr_b32 s30, s30, 26
	s_add_i32 s30, s1, s30
	s_ashr_i32 s31, s30, 6
	s_lshl_b32 s31, s31, 3
	s_sub_i32 s34, 0x100, s31
	s_min_i32 s34, s34, 8
	s_andn2_b32 s30, s30, 63
	s_sub_i32 s1, s1, s30
	s_mov_b64 s[54:55], -1
	s_ff1_i32_b32 s49, s34
	s_lshr_b32 s48, s1, s49
	s_add_i32 s49, s34, -1
	s_and_b32 s1, s1, s49


;     __host__ __device__ bool next(int i, Unit& u) const {
;     ...
;         u.pm = fm + ((wgid % nig) % gsz); u.pn = (wgid % nig) / gsz; return true;
	s_add_i32 s50, s31, s1

;     __host__ __device__ bool next(int i, Unit& u) const {
;     ...
;         int wgid = (int)L; { const int q = nwg / NXCD, r = nwg % NXCD, xcd = wgid % NXCD, off = wgid / NXCD; wgid = (xcd < r ? xcd * (q + 1) : r * (q + 1) + (xcd - r) * q) + off; }
;         const int nig = WGM * nN, gid = wgid / nig, fm = gid * WGM, gsz = (nM - fm) < WGM ? (nM - fm) : WGM;
;         u.pm = fm + ((wgid % nig) % gsz); u.pn = (wgid % nig) / gsz; return true;
.LBB0_289:
	s_ashr_i32 s30, s30, 3
	s_add_i32 s30, s34, s30
	s_ashr_i32 s31, s30, 31
	s_lshr_b32 s31, s31, 21
	s_add_i32 s31, s30, s31
	s_ashr_i32 s34, s31, 11
	s_lshl_b32 s34, s34, 3
	s_sub_i32 s35, 4, s34
	s_min_i32 s35, s35, 8
	s_and_b32 s31, s31, 0xfffff800
	s_sub_i32 s30, s30, s31
	s_ff1_i32_b32 s44, s35
	s_lshr_b32 s42, s30, s44
	s_add_i32 s44, s35, -1
	s_and_b32 s30, s30, s44


;     __host__ __device__ bool next(int i, Unit& u) const {
;     ...
;         u.pm = fm + ((wgid % nig) % gsz); u.pn = (wgid % nig) / gsz; return true;
	s_add_i32 s44, s34, s30
	s_mov_b64 s[48:49], -1

;     __host__ __device__ bool next(int i, Unit& u) const {
;     ...
;         int wgid = (int)L; { const int q = nwg / NXCD, r = nwg % NXCD, xcd = wgid % NXCD, off = wgid / NXCD; wgid = (xcd < r ? xcd * (q + 1) : r * (q + 1) + (xcd - r) * q) + off; }
;         const int nig = WGM * nN, gid = wgid / nig, fm = gid * WGM, gsz = (nM - fm) < WGM ? (nM - fm) : WGM;
;         u.pm = fm + ((wgid % nig) % gsz); u.pn = (wgid % nig) / gsz; return true;
.LBB0_451:
	s_ashr_i32 s30, s30, 3
	s_add_i32 s30, s34, s30
	s_ashr_i32 s31, s30, 31
	s_lshr_b32 s31, s31, 27
	s_add_i32 s31, s30, s31
	s_ashr_i32 s34, s31, 5
	s_lshl_b32 s34, s34, 3
	s_sub_i32 s35, 0x100, s34
	s_min_i32 s35, s35, 8
	s_andn2_b32 s31, s31, 31
	s_sub_i32 s30, s30, s31
	s_mov_b64 s[54:55], -1
	s_ff1_i32_b32 s50, s35
	s_lshr_b32 s48, s30, s50
	s_add_i32 s50, s35, -1
	s_and_b32 s30, s30, s50


;     __host__ __device__ bool next(int i, Unit& u) const {
;     ...
;         u.pm = fm + ((wgid % nig) % gsz); u.pn = (wgid % nig) / gsz; return true;
	s_add_i32 s50, s34, s30

;     __host__ __device__ bool next(int i, Unit& u) const {
;     ...
;         int wgid = (int)L; { const int q = nwg / NXCD, r = nwg % NXCD, xcd = wgid % NXCD, off = wgid / NXCD; wgid = (xcd < r ? xcd * (q + 1) : r * (q + 1) + (xcd - r) * q) + off; }
;         const int nig = WGM * nN, gid = wgid / nig, fm = gid * WGM, gsz = (nM - fm) < WGM ? (nM - fm) : WGM;
;         u.pm = fm + ((wgid % nig) % gsz); u.pn = (wgid % nig) / gsz; return true;
.LBB0_485:
	s_ashr_i32 s30, s30, 3
	s_add_i32 s30, s34, s30
	s_ashr_i32 s31, s30, 31
	s_lshr_b32 s31, s31, 27
	s_add_i32 s31, s30, s31
	s_ashr_i32 s34, s31, 5
	s_lshl_b32 s34, s34, 3
	s_sub_i32 s35, 0x100, s34
	s_min_i32 s35, s35, 8
	s_andn2_b32 s31, s31, 31
	s_sub_i32 s30, s30, s31
	s_ff1_i32_b32 s46, s35
	s_lshr_b32 s44, s30, s46
	s_add_i32 s46, s35, -1
	s_and_b32 s30, s30, s46


;     __host__ __device__ bool next(int i, Unit& u) const {
;     ...
;         u.pm = fm + ((wgid % nig) % gsz); u.pn = (wgid % nig) / gsz; return true;
	s_add_i32 s46, s34, s30
	s_mov_b64 s[48:49], -1

;     __host__ __device__ bool next(int i, Unit& u) const {
;     ...
;         int wgid = (int)L; { const int q = nwg / NXCD, r = nwg % NXCD, xcd = wgid % NXCD, off = wgid / NXCD; wgid = (xcd < r ? xcd * (q + 1) : r * (q + 1) + (xcd - r) * q) + off; }
;         const int nig = WGM * nN, gid = wgid / nig, fm = gid * WGM, gsz = (nM - fm) < WGM ? (nM - fm) : WGM;
;         u.pm = fm + ((wgid % nig) % gsz); u.pn = (wgid % nig) / gsz; return true;
.LBB0_520:
	s_ashr_i32 s30, s30, 3
	s_add_i32 s30, s34, s30
	s_ashr_i32 s31, s30, 31
	s_lshr_b32 s31, s31, 27
	s_add_i32 s31, s30, s31
	s_ashr_i32 s34, s31, 5
	s_lshl_b32 s34, s34, 3
	s_sub_i32 s35, 0x100, s34
	s_min_i32 s35, s35, 8
	s_andn2_b32 s31, s31, 31
	s_sub_i32 s30, s30, s31
	s_ff1_i32_b32 s44, s35
	s_lshr_b32 s42, s30, s44
	s_add_i32 s44, s35, -1
	s_and_b32 s30, s30, s44


;     __host__ __device__ bool next(int i, Unit& u) const {
;     ...
;         u.pm = fm + ((wgid % nig) % gsz); u.pn = (wgid % nig) / gsz; return true;
	s_add_i32 s44, s34, s30
	s_mov_b64 s[46:47], -1

;     __host__ __device__ bool next(int i, Unit& u) const {
;     ...
;         int wgid = (int)L; { const int q = nwg / NXCD, r = nwg % NXCD, xcd = wgid % NXCD, off = wgid / NXCD; wgid = (xcd < r ? xcd * (q + 1) : r * (q + 1) + (xcd - r) * q) + off; }
;         const int nig = WGM * nN, gid = wgid / nig, fm = gid * WGM, gsz = (nM - fm) < WGM ? (nM - fm) : WGM;
;         u.pm = fm + ((wgid % nig) % gsz); u.pn = (wgid % nig) / gsz; return true;
.LBB0_555:
	s_ashr_i32 s30, s30, 3
	s_add_i32 s30, s34, s30
	s_ashr_i32 s31, s30, 31
	s_lshr_b32 s31, s31, 26
	s_add_i32 s31, s30, s31
	s_ashr_i32 s34, s31, 6
	s_lshl_b32 s34, s34, 3
	s_sub_i32 s35, 0x100, s34
	s_min_i32 s35, s35, 8
	s_andn2_b32 s31, s31, 63
	s_sub_i32 s30, s30, s31
	s_ff1_i32_b32 s42, s35
	s_lshr_b32 s40, s30, s42
	s_add_i32 s42, s35, -1
	s_and_b32 s30, s30, s42


;     __host__ __device__ bool next(int i, Unit& u) const {
;     ...
;         u.pm = fm + ((wgid % nig) % gsz); u.pn = (wgid % nig) / gsz; return true;
	s_add_i32 s42, s34, s30
	s_mov_b64 s[44:45], -1
